# P3 epilogue: leading half's alignment barrier moved below its first gate and partial-sum loads (on top of nt hints for merge-gate and prologue loads)
# speedup vs baseline: 1.0047x; 1.0047x over previous
; #define PG8_STAGE(bufoff, gbase, voff) do { _Pragma("unroll") for (int _i = 0; _i < 2; ++_i) \
;         __builtin_amdgcn_global_load_lds((const unsigned*)((const char*)(gbase) + (voff)[_i]), (PG8_LAS unsigned*)(lds + (bufoff) + ldsw + _i * 8192), 16, 0, 0); } while (0)
; #define PG8_LDA(dst, b, h) do { _Pragma("unroll") for (int m = 0; m < 4; ++m) _Pragma("unroll") for (int k = 0; k < 2; ++k) dst[m][k] = *(const PG8_LAS bf16x8*)(lds + PG8_SA(b, h) + aoff + m * 2048 + k * 1024); } while (0)
; #define PG8_LDB(dst, b, h) do { _Pragma("unroll") for (int n = 0; n < 2; ++n) _Pragma("unroll") for (int k = 0; k < 2; ++k) dst[n][k] = *(const PG8_LAS bf16x8*)(lds + PG8_SB(b, h) + boff + n * 2048 + k * 1024); } while (0)
; #define PG8_MMA(ai, bj, At, Bt) do { __builtin_amdgcn_s_setprio(1); _Pragma("unroll") for (int m = 0; m < 4; ++m) _Pragma("unroll") for (int n = 0; n < 2; ++n) _Pragma("unroll") for (int k = 0; k < 2; ++k) \
;         acc[ai][bj][m][n] = __builtin_amdgcn_mfma_f32_16x16x32_bf16(Bt[n][k], At[m][k], acc[ai][bj][m][n], 0, 0, 0); __builtin_amdgcn_s_setprio(0); } while (0)
; #define PG8_WAIT_V(n) asm volatile("s_waitcnt vmcnt(" #n ")" ::: "memory")
; #define PG8_WAIT_L(n) asm volatile("s_waitcnt lgkmcnt(" #n ")" ::: "memory")
; #define PG8_BAR __builtin_amdgcn_s_barrier()
; template <class Epi, class Sched, bool ALIGN_EPI = false, bool SP2 = false>
; __device__ __forceinline__ void gemm_phase(PG8_LAS unsigned char* lds, const Gemm g, const Sched& S, const Epi& E) {
;     ...
;         for (int t = 0; t < nt; t += 2) {
;             const bool last = (t == nt - 2);
;             const char* a1 = cA + (size_t)(t + 1) * kstep;
;             const char* a2 = last ? nA : cA + (size_t)(t + 2) * kstep; const char* b2 = last ? nB : cB + (size_t)(t + 2) * kstep;
;             const char* a3 = a2 + kstep; const char* b3 = b2 + kstep;
;             if constexpr (SP2) {
;             PG8_LDB(B0, 0, 0); PG8_LDB(B1, 0, 1); PG8_SCHED; PG8_LDA(At, 0, 0); PG8_STAGE(PG8_SA(1, 1), a1 + hstep, voffA);
;             PG8_WAIT_V(8); PG8_WAIT_L(0); PG8_BAR; PG8_MMA(0, 0, At, B0); PG8_MMA(0, 1, At, B1); PG8_BAR; PG8_SCHED;
;             PG8_LDA(At, 0, 1); PG8_STAGE(PG8_SB(0, 0), b2, voffB); PG8_STAGE(PG8_SB(0, 1), b2 + hstep, voffB); PG8_STAGE(PG8_SA(0, 0), a2, voffA);
;             PG8_WAIT_V(8); PG8_WAIT_L(0); PG8_BAR; PG8_MMA(1, 0, At, B0); PG8_MMA(1, 1, At, B1); PG8_BAR; PG8_SCHED;
.LBB0_395:
	s_add_u32 s33, s6, 0xfffe0080
	s_addc_u32 s48, s7, -1
	s_add_i32 s99, 0, 0x10000
	s_cmp_eq_u32 s98, 4
	s_cselect_b32 s61, s23, s48
	s_cselect_b32 s60, s47, s33
	s_cselect_b32 s49, s25, s97
	s_cselect_b32 s48, s27, s58
	s_add_i32 s33, 0, 0x14000
	v_add_u32_e32 v136, s99, v245
	v_add_u32_e32 v156, s33, v245
	ds_read_b128 v[120:123], v136
	ds_read_b128 v[124:127], v136 offset:1024
	ds_read_b128 v[132:135], v136 offset:2048
	ds_read_b128 v[136:139], v136 offset:3072
	ds_read_b128 v[144:147], v156
	ds_read_b128 v[148:151], v156 offset:1024
	ds_read_b128 v[152:155], v156 offset:2048
	ds_read_b128 v[156:159], v156 offset:3072
	v_lshl_add_u64 v[212:213], s[6:7], 0, v[208:209]
	s_add_i32 m0, s40, 0xc000
	ds_read_b128 v[160:163], v246
	ds_read_b128 v[164:167], v246 offset:1024
	ds_read_b128 v[168:171], v246 offset:2048
	ds_read_b128 v[172:175], v246 offset:3072
	ds_read_b128 v[176:179], v246 offset:4096
	ds_read_b128 v[180:183], v246 offset:5120
	ds_read_b128 v[184:187], v246 offset:6144
	ds_read_b128 v[188:191], v246 offset:7168
	global_load_lds_dwordx4 v[212:213], off
	v_lshl_add_u64 v[212:213], s[6:7], 0, v[210:211]
	s_add_i32 m0, s40, 0xe000
	s_nop 0
	global_load_lds_dwordx4 v[212:213], off
	s_waitcnt vmcnt(8)
	s_waitcnt lgkmcnt(0)
	s_barrier
	s_setprio 1
	s_waitcnt lgkmcnt(0)
	v_mfma_f32_16x16x32_bf16 v[140:143], v[120:123], v[160:163], v[140:143]
	v_mfma_f32_16x16x32_bf16 v[128:131], v[132:135], v[160:163], v[128:131]
	v_mfma_f32_16x16x32_bf16 v[108:111], v[120:123], v[168:171], v[108:111]
	v_mfma_f32_16x16x32_bf16 v[104:107], v[132:135], v[168:171], v[104:107]
	v_mfma_f32_16x16x32_bf16 v[92:95], v[120:123], v[176:179], v[92:95]
	v_mfma_f32_16x16x32_bf16 v[88:91], v[132:135], v[176:179], v[88:91]
	v_mfma_f32_16x16x32_bf16 v[76:79], v[120:123], v[184:187], v[76:79]
	v_mfma_f32_16x16x32_bf16 v[72:75], v[132:135], v[184:187], v[72:75]
	v_mfma_f32_16x16x32_bf16 v[140:143], v[124:127], v[164:167], v[140:143]
	v_mfma_f32_16x16x32_bf16 v[128:131], v[136:139], v[164:167], v[128:131]
	v_mfma_f32_16x16x32_bf16 v[108:111], v[124:127], v[172:175], v[108:111]
	v_mfma_f32_16x16x32_bf16 v[104:107], v[136:139], v[172:175], v[104:107]
	v_mfma_f32_16x16x32_bf16 v[92:95], v[124:127], v[180:183], v[92:95]
	v_mfma_f32_16x16x32_bf16 v[88:91], v[136:139], v[180:183], v[88:91]
	v_mfma_f32_16x16x32_bf16 v[76:79], v[124:127], v[188:191], v[76:79]
	v_mfma_f32_16x16x32_bf16 v[72:75], v[136:139], v[188:191], v[72:75]
	s_setprio 0
	s_setprio 1
	v_mfma_f32_16x16x32_bf16 v[116:119], v[144:147], v[160:163], v[116:119]
	v_mfma_f32_16x16x32_bf16 v[112:115], v[152:155], v[160:163], v[112:115]
	v_mfma_f32_16x16x32_bf16 v[100:103], v[144:147], v[168:171], v[100:103]
	v_mfma_f32_16x16x32_bf16 v[96:99], v[152:155], v[168:171], v[96:99]
	v_mfma_f32_16x16x32_bf16 v[84:87], v[144:147], v[176:179], v[84:87]
	v_mfma_f32_16x16x32_bf16 v[80:83], v[152:155], v[176:179], v[80:83]
	v_mfma_f32_16x16x32_bf16 v[68:71], v[144:147], v[184:187], v[68:71]
	v_mfma_f32_16x16x32_bf16 v[64:67], v[152:155], v[184:187], v[64:67]
	v_mfma_f32_16x16x32_bf16 v[116:119], v[148:151], v[164:167], v[116:119]
	v_mfma_f32_16x16x32_bf16 v[112:115], v[156:159], v[164:167], v[112:115]
	v_mfma_f32_16x16x32_bf16 v[100:103], v[148:151], v[172:175], v[100:103]
	v_mfma_f32_16x16x32_bf16 v[96:99], v[156:159], v[172:175], v[96:99]
	v_mfma_f32_16x16x32_bf16 v[84:87], v[148:151], v[180:183], v[84:87]
	v_mfma_f32_16x16x32_bf16 v[80:83], v[156:159], v[180:183], v[80:83]
	v_mfma_f32_16x16x32_bf16 v[68:71], v[148:151], v[188:191], v[68:71]
	v_mfma_f32_16x16x32_bf16 v[64:67], v[156:159], v[188:191], v[64:67]
	s_setprio 0
	s_barrier
	s_add_i32 s99, s99, s39
	v_lshl_add_u64 v[212:213], s[48:49], 0, v[204:205]
	s_mov_b32 m0, s99
	ds_read_b128 v[160:163], v246 offset:16384
	ds_read_b128 v[164:167], v246 offset:17408
	ds_read_b128 v[168:171], v246 offset:18432
	ds_read_b128 v[172:175], v246 offset:19456
	ds_read_b128 v[176:179], v246 offset:20480
	ds_read_b128 v[180:183], v246 offset:21504
	ds_read_b128 v[184:187], v246 offset:22528
	ds_read_b128 v[188:191], v246 offset:23552
	global_load_lds_dwordx4 v[212:213], off
	s_add_i32 m0, s99, 0x2000
	s_add_u32 vcc_lo, s48, 0x20000
	v_lshl_add_u64 v[214:215], s[48:49], 0, v[200:201]
	s_addc_u32 vcc_hi, s49, 0
	s_add_i32 s33, s33, s39
	global_load_lds_dwordx4 v[214:215], off
	v_lshl_add_u64 v[216:217], vcc, 0, v[204:205]
	s_mov_b32 m0, s33
	v_lshl_add_u64 v[218:219], s[60:61], 0, v[202:203]
	global_load_lds_dwordx4 v[216:217], off
	v_lshl_add_u64 v[216:217], vcc, 0, v[200:201]
	s_add_i32 m0, s33, 0x2000
	s_nop 0
	global_load_lds_dwordx4 v[216:217], off
	v_lshl_add_u64 v[216:217], s[60:61], 0, v[206:207]
	s_mov_b32 m0, s40
	s_nop 0
	global_load_lds_dwordx4 v[216:217], off
	s_mov_b32 m0, s41
	s_nop 0
	global_load_lds_dwordx4 v[218:219], off
	s_waitcnt vmcnt(8)
	s_waitcnt lgkmcnt(0)
	s_barrier
; #define PG8_STAGE(bufoff, gbase, voff) do { _Pragma("unroll") for (int _i = 0; _i < 2; ++_i) \
;         __builtin_amdgcn_global_load_lds((const unsigned*)((const char*)(gbase) + (voff)[_i]), (PG8_LAS unsigned*)(lds + (bufoff) + ldsw + _i * 8192), 16, 0, 0); } while (0)
; #define PG8_LDA(dst, b, h) do { _Pragma("unroll") for (int m = 0; m < 4; ++m) _Pragma("unroll") for (int k = 0; k < 2; ++k) dst[m][k] = *(const PG8_LAS bf16x8*)(lds + PG8_SA(b, h) + aoff + m * 2048 + k * 1024); } while (0)
; #define PG8_LDB(dst, b, h) do { _Pragma("unroll") for (int n = 0; n < 2; ++n) _Pragma("unroll") for (int k = 0; k < 2; ++k) dst[n][k] = *(const PG8_LAS bf16x8*)(lds + PG8_SB(b, h) + boff + n * 2048 + k * 1024); } while (0)
; #define PG8_MMA(ai, bj, At, Bt) do { __builtin_amdgcn_s_setprio(1); _Pragma("unroll") for (int m = 0; m < 4; ++m) _Pragma("unroll") for (int n = 0; n < 2; ++n) _Pragma("unroll") for (int k = 0; k < 2; ++k) \
;         acc[ai][bj][m][n] = __builtin_amdgcn_mfma_f32_16x16x32_bf16(Bt[n][k], At[m][k], acc[ai][bj][m][n], 0, 0, 0); __builtin_amdgcn_s_setprio(0); } while (0)
; #define PG8_WAIT_V(n) asm volatile("s_waitcnt vmcnt(" #n ")" ::: "memory")
; #define PG8_WAIT_L(n) asm volatile("s_waitcnt lgkmcnt(" #n ")" ::: "memory")
; #define PG8_BAR __builtin_amdgcn_s_barrier()
; #define PG8_SCHED __builtin_amdgcn_sched_barrier(0)
; template <class Epi, class Sched, bool ALIGN_EPI = false, bool SP2 = false>
; __device__ __forceinline__ void gemm_phase(PG8_LAS unsigned char* lds, const Gemm g, const Sched& S, const Epi& E) {
;     ...
;             PG8_WAIT_V(8); PG8_WAIT_L(0); PG8_BAR; PG8_MMA(1, 0, At, B0); PG8_MMA(1, 1, At, B1); PG8_BAR; PG8_SCHED;
;             PG8_LDB(B0, 1, 0); PG8_LDB(B1, 1, 1); PG8_SCHED; PG8_LDA(At, 1, 0); PG8_STAGE(PG8_SA(0, 1), a2 + hstep, voffA);
;             PG8_WAIT_V(8); PG8_WAIT_L(0); PG8_BAR; PG8_MMA(0, 0, At, B0); PG8_MMA(0, 1, At, B1); PG8_BAR; PG8_SCHED;
	s_setprio 1
	s_waitcnt lgkmcnt(0)
	v_mfma_f32_16x16x32_bf16 v[60:63], v[120:123], v[160:163], v[60:63]
	v_mfma_f32_16x16x32_bf16 v[56:59], v[132:135], v[160:163], v[56:59]
	v_mfma_f32_16x16x32_bf16 v[44:47], v[120:123], v[168:171], v[44:47]
	v_mfma_f32_16x16x32_bf16 v[40:43], v[132:135], v[168:171], v[40:43]
	v_mfma_f32_16x16x32_bf16 v[28:31], v[120:123], v[176:179], v[28:31]
	v_mfma_f32_16x16x32_bf16 v[24:27], v[132:135], v[176:179], v[24:27]
	v_mfma_f32_16x16x32_bf16 v[12:15], v[120:123], v[184:187], v[12:15]
	v_mfma_f32_16x16x32_bf16 v[8:11], v[132:135], v[184:187], v[8:11]
	v_mfma_f32_16x16x32_bf16 v[60:63], v[124:127], v[164:167], v[60:63]
	v_mfma_f32_16x16x32_bf16 v[56:59], v[136:139], v[164:167], v[56:59]
	v_mfma_f32_16x16x32_bf16 v[44:47], v[124:127], v[172:175], v[44:47]
	v_mfma_f32_16x16x32_bf16 v[40:43], v[136:139], v[172:175], v[40:43]
	v_mfma_f32_16x16x32_bf16 v[28:31], v[124:127], v[180:183], v[28:31]
	v_mfma_f32_16x16x32_bf16 v[24:27], v[136:139], v[180:183], v[24:27]
	v_mfma_f32_16x16x32_bf16 v[12:15], v[124:127], v[188:191], v[12:15]
	v_mfma_f32_16x16x32_bf16 v[8:11], v[136:139], v[188:191], v[8:11]
	s_setprio 0
	s_setprio 1
	v_mfma_f32_16x16x32_bf16 v[52:55], v[144:147], v[160:163], v[52:55]
	v_mfma_f32_16x16x32_bf16 v[48:51], v[152:155], v[160:163], v[48:51]
	v_mfma_f32_16x16x32_bf16 v[36:39], v[144:147], v[168:171], v[36:39]
	v_mfma_f32_16x16x32_bf16 v[32:35], v[152:155], v[168:171], v[32:35]
	v_mfma_f32_16x16x32_bf16 v[20:23], v[144:147], v[176:179], v[20:23]
	v_mfma_f32_16x16x32_bf16 v[16:19], v[152:155], v[176:179], v[16:19]
	v_mfma_f32_16x16x32_bf16 v[4:7], v[144:147], v[184:187], v[4:7]
	v_mfma_f32_16x16x32_bf16 v[0:3], v[152:155], v[184:187], v[0:3]
	v_mfma_f32_16x16x32_bf16 v[52:55], v[148:151], v[164:167], v[52:55]
	v_mfma_f32_16x16x32_bf16 v[48:51], v[156:159], v[164:167], v[48:51]
	v_mfma_f32_16x16x32_bf16 v[36:39], v[148:151], v[172:175], v[36:39]
	v_mfma_f32_16x16x32_bf16 v[32:35], v[156:159], v[172:175], v[32:35]
	v_mfma_f32_16x16x32_bf16 v[20:23], v[148:151], v[180:183], v[20:23]
	v_mfma_f32_16x16x32_bf16 v[16:19], v[156:159], v[180:183], v[16:19]
	v_mfma_f32_16x16x32_bf16 v[4:7], v[148:151], v[188:191], v[4:7]
	v_mfma_f32_16x16x32_bf16 v[0:3], v[156:159], v[188:191], v[0:3]
	s_setprio 0
	s_barrier
	s_add_i32 s33, 0, 0x18000
	s_add_i32 s99, 0, 0x1c000
	v_add_u32_e32 v136, s33, v245
	v_add_u32_e32 v156, s99, v245
	ds_read_b128 v[120:123], v136
	ds_read_b128 v[124:127], v136 offset:1024
	ds_read_b128 v[132:135], v136 offset:2048
	ds_read_b128 v[136:139], v136 offset:3072
	ds_read_b128 v[144:147], v156
	ds_read_b128 v[148:151], v156 offset:1024
	ds_read_b128 v[152:155], v156 offset:2048
	ds_read_b128 v[156:159], v156 offset:3072
	s_add_u32 s60, s60, 0x20000
	s_addc_u32 s61, s61, 0
	s_mov_b32 m0, s50
	v_lshl_add_u64 v[220:221], s[60:61], 0, v[206:207]
	ds_read_b128 v[160:163], v246 offset:32768
	ds_read_b128 v[164:167], v246 offset:33792
	ds_read_b128 v[168:171], v246 offset:34816
	ds_read_b128 v[172:175], v246 offset:35840
	ds_read_b128 v[176:179], v246 offset:36864
	ds_read_b128 v[180:183], v246 offset:37888
	ds_read_b128 v[184:187], v246 offset:38912
	ds_read_b128 v[188:191], v246 offset:39936
	global_load_lds_dwordx4 v[220:221], off
	v_lshl_add_u64 v[220:221], s[60:61], 0, v[202:203]
	s_mov_b32 m0, s51
	s_nop 0
	global_load_lds_dwordx4 v[220:221], off
	s_waitcnt vmcnt(8)
	s_waitcnt lgkmcnt(0)
	s_barrier
	s_setprio 1
	s_waitcnt lgkmcnt(0)
	v_mfma_f32_16x16x32_bf16 v[140:143], v[120:123], v[160:163], v[140:143]
	v_mfma_f32_16x16x32_bf16 v[128:131], v[132:135], v[160:163], v[128:131]
	v_mfma_f32_16x16x32_bf16 v[108:111], v[120:123], v[168:171], v[108:111]
	v_mfma_f32_16x16x32_bf16 v[104:107], v[132:135], v[168:171], v[104:107]
	v_mfma_f32_16x16x32_bf16 v[92:95], v[120:123], v[176:179], v[92:95]
	v_mfma_f32_16x16x32_bf16 v[88:91], v[132:135], v[176:179], v[88:91]
	v_mfma_f32_16x16x32_bf16 v[76:79], v[120:123], v[184:187], v[76:79]
	v_mfma_f32_16x16x32_bf16 v[72:75], v[132:135], v[184:187], v[72:75]
	v_mfma_f32_16x16x32_bf16 v[140:143], v[124:127], v[164:167], v[140:143]
	v_mfma_f32_16x16x32_bf16 v[128:131], v[136:139], v[164:167], v[128:131]
	v_mfma_f32_16x16x32_bf16 v[108:111], v[124:127], v[172:175], v[108:111]
	v_mfma_f32_16x16x32_bf16 v[104:107], v[136:139], v[172:175], v[104:107]
	v_mfma_f32_16x16x32_bf16 v[92:95], v[124:127], v[180:183], v[92:95]
	v_mfma_f32_16x16x32_bf16 v[88:91], v[136:139], v[180:183], v[88:91]
	v_mfma_f32_16x16x32_bf16 v[76:79], v[124:127], v[188:191], v[76:79]
	v_mfma_f32_16x16x32_bf16 v[72:75], v[136:139], v[188:191], v[72:75]
	s_setprio 0
	s_setprio 1
	v_mfma_f32_16x16x32_bf16 v[116:119], v[144:147], v[160:163], v[116:119]
	v_mfma_f32_16x16x32_bf16 v[112:115], v[152:155], v[160:163], v[112:115]
	v_mfma_f32_16x16x32_bf16 v[100:103], v[144:147], v[168:171], v[100:103]
	v_mfma_f32_16x16x32_bf16 v[96:99], v[152:155], v[168:171], v[96:99]
	v_mfma_f32_16x16x32_bf16 v[84:87], v[144:147], v[176:179], v[84:87]
	v_mfma_f32_16x16x32_bf16 v[80:83], v[152:155], v[176:179], v[80:83]
	v_mfma_f32_16x16x32_bf16 v[68:71], v[144:147], v[184:187], v[68:71]
	v_mfma_f32_16x16x32_bf16 v[64:67], v[152:155], v[184:187], v[64:67]
	v_mfma_f32_16x16x32_bf16 v[116:119], v[148:151], v[164:167], v[116:119]
	v_mfma_f32_16x16x32_bf16 v[112:115], v[156:159], v[164:167], v[112:115]
	v_mfma_f32_16x16x32_bf16 v[100:103], v[148:151], v[172:175], v[100:103]
	v_mfma_f32_16x16x32_bf16 v[96:99], v[156:159], v[172:175], v[96:99]
	v_mfma_f32_16x16x32_bf16 v[84:87], v[148:151], v[180:183], v[84:87]
	v_mfma_f32_16x16x32_bf16 v[80:83], v[156:159], v[180:183], v[80:83]
	v_mfma_f32_16x16x32_bf16 v[68:71], v[148:151], v[188:191], v[68:71]
	v_mfma_f32_16x16x32_bf16 v[64:67], v[156:159], v[188:191], v[64:67]
	s_setprio 0
	s_barrier
; #define PG8_STAGE(bufoff, gbase, voff) do { _Pragma("unroll") for (int _i = 0; _i < 2; ++_i) \
;         __builtin_amdgcn_global_load_lds((const unsigned*)((const char*)(gbase) + (voff)[_i]), (PG8_LAS unsigned*)(lds + (bufoff) + ldsw + _i * 8192), 16, 0, 0); } while (0)
; #define PG8_LDA(dst, b, h) do { _Pragma("unroll") for (int m = 0; m < 4; ++m) _Pragma("unroll") for (int k = 0; k < 2; ++k) dst[m][k] = *(const PG8_LAS bf16x8*)(lds + PG8_SA(b, h) + aoff + m * 2048 + k * 1024); } while (0)
; #define PG8_MMA(ai, bj, At, Bt) do { __builtin_amdgcn_s_setprio(1); _Pragma("unroll") for (int m = 0; m < 4; ++m) _Pragma("unroll") for (int n = 0; n < 2; ++n) _Pragma("unroll") for (int k = 0; k < 2; ++k) \
;         acc[ai][bj][m][n] = __builtin_amdgcn_mfma_f32_16x16x32_bf16(Bt[n][k], At[m][k], acc[ai][bj][m][n], 0, 0, 0); __builtin_amdgcn_s_setprio(0); } while (0)
; #define PG8_WAIT_V(n) asm volatile("s_waitcnt vmcnt(" #n ")" ::: "memory")
; #define PG8_WAIT_L(n) asm volatile("s_waitcnt lgkmcnt(" #n ")" ::: "memory")
; #define PG8_BAR __builtin_amdgcn_s_barrier()
; #define PG8_SCHED __builtin_amdgcn_sched_barrier(0)
;     __device__ __forceinline__ void operator()(const f32x4 (&acc)[2][2][4][2], const Unit& u, int wr, int wc, int fr, int fq) const {
;         const int row0 = u.pm * BM + wr * 64 + fr, col0 = u.pn * BM + wc * 32 + 8 * fq, br = u.br;
; #pragma unroll
;         for (int ai = 0; ai < 2; ++ai) {
;             u32x4 gv[4][2], pv[4][2];
; #pragma unroll
;             for (int m = 0; m < 4; ++m)
; #pragma unroll
;                 for (int bj = 0; bj < 2; ++bj) { const int row = row0 + ai * HALF + m * 16, col = col0 + bj * HALF;
;                     gv[m][bj] = *(const u32x4*)(P + PB(8448 + br * 1024 + col) + (size_t)row * 64);
;                     if (br > 0) pv[m][bj] = *(const u32x4*)(MIX + (size_t)row * 1024 + col); else pv[m][bj] = (u32x4){0u, 0u, 0u, 0u}; }
; template <class Epi, class Sched, bool ALIGN_EPI = false, bool SP2 = false>
; __device__ __forceinline__ void gemm_phase(PG8_LAS unsigned char* lds, const Gemm g, const Sched& S, const Epi& E) {
;     ...
;             PG8_LDA(At, 1, 1); PG8_STAGE(PG8_SB(1, 0), b3, voffB); PG8_STAGE(PG8_SB(1, 1), b3 + hstep, voffB); PG8_STAGE(PG8_SA(1, 0), a3, voffA);
;             PG8_WAIT_V(8); PG8_WAIT_L(0); PG8_BAR; PG8_MMA(1, 0, At, B0); PG8_MMA(1, 1, At, B1); PG8_BAR; PG8_SCHED;
	s_add_i32 s33, s33, s39
	v_lshl_add_u64 v[212:213], v[212:213], 0, s[64:65]
	s_mov_b32 m0, s33
	ds_read_b128 v[160:163], v246 offset:49152
	ds_read_b128 v[164:167], v246 offset:50176
	ds_read_b128 v[168:171], v246 offset:51200
	ds_read_b128 v[172:175], v246 offset:52224
	ds_read_b128 v[176:179], v246 offset:53248
	ds_read_b128 v[180:183], v246 offset:54272
	ds_read_b128 v[184:187], v246 offset:55296
	ds_read_b128 v[188:191], v246 offset:56320
	global_load_lds_dwordx4 v[212:213], off
	s_add_i32 m0, s33, 0x2000
	s_add_u32 s48, s48, 0x20080
	v_lshl_add_u64 v[212:213], v[214:215], 0, s[64:65]
	s_addc_u32 s49, s49, 0
	s_add_i32 s33, s99, s39
	global_load_lds_dwordx4 v[212:213], off
	v_lshl_add_u64 v[212:213], s[48:49], 0, v[204:205]
	s_mov_b32 m0, s33
	s_nop 0
	global_load_lds_dwordx4 v[212:213], off
	v_lshl_add_u64 v[212:213], s[48:49], 0, v[200:201]
	s_add_i32 m0, s33, 0x2000
	s_nop 0
	global_load_lds_dwordx4 v[212:213], off
	v_lshl_add_u64 v[212:213], v[216:217], 0, s[64:65]
	s_mov_b32 m0, s57
	s_nop 0
	global_load_lds_dwordx4 v[212:213], off
	v_lshl_add_u64 v[212:213], v[218:219], 0, s[64:65]
	s_mov_b32 m0, s59
	s_nop 0
	global_load_lds_dwordx4 v[212:213], off
	s_waitcnt vmcnt(8)
	s_waitcnt lgkmcnt(0)
	s_barrier
	s_setprio 1
	s_waitcnt lgkmcnt(0)
	v_mfma_f32_16x16x32_bf16 v[60:63], v[120:123], v[160:163], v[60:63]
	v_mfma_f32_16x16x32_bf16 v[56:59], v[132:135], v[160:163], v[56:59]
	v_mfma_f32_16x16x32_bf16 v[44:47], v[120:123], v[168:171], v[44:47]
	v_mfma_f32_16x16x32_bf16 v[40:43], v[132:135], v[168:171], v[40:43]
	v_mfma_f32_16x16x32_bf16 v[28:31], v[120:123], v[176:179], v[28:31]
	v_mfma_f32_16x16x32_bf16 v[24:27], v[132:135], v[176:179], v[24:27]
	v_mfma_f32_16x16x32_bf16 v[12:15], v[120:123], v[184:187], v[12:15]
	v_mfma_f32_16x16x32_bf16 v[8:11], v[132:135], v[184:187], v[8:11]
	v_mfma_f32_16x16x32_bf16 v[60:63], v[124:127], v[164:167], v[60:63]
	v_mfma_f32_16x16x32_bf16 v[56:59], v[136:139], v[164:167], v[56:59]
	v_mfma_f32_16x16x32_bf16 v[44:47], v[124:127], v[172:175], v[44:47]
	v_mfma_f32_16x16x32_bf16 v[40:43], v[136:139], v[172:175], v[40:43]
	v_mfma_f32_16x16x32_bf16 v[28:31], v[124:127], v[180:183], v[28:31]
	v_mfma_f32_16x16x32_bf16 v[24:27], v[136:139], v[180:183], v[24:27]
	v_mfma_f32_16x16x32_bf16 v[12:15], v[124:127], v[188:191], v[12:15]
	v_mfma_f32_16x16x32_bf16 v[8:11], v[136:139], v[188:191], v[8:11]
	s_setprio 0
	s_setprio 1
	v_mfma_f32_16x16x32_bf16 v[52:55], v[144:147], v[160:163], v[52:55]
	v_mfma_f32_16x16x32_bf16 v[48:51], v[152:155], v[160:163], v[48:51]
	v_mfma_f32_16x16x32_bf16 v[36:39], v[144:147], v[168:171], v[36:39]
	v_mfma_f32_16x16x32_bf16 v[32:35], v[152:155], v[168:171], v[32:35]
	v_mfma_f32_16x16x32_bf16 v[20:23], v[144:147], v[176:179], v[20:23]
	v_mfma_f32_16x16x32_bf16 v[16:19], v[152:155], v[176:179], v[16:19]
	v_mfma_f32_16x16x32_bf16 v[4:7], v[144:147], v[184:187], v[4:7]
	v_mfma_f32_16x16x32_bf16 v[0:3], v[152:155], v[184:187], v[0:3]
	v_mfma_f32_16x16x32_bf16 v[52:55], v[148:151], v[164:167], v[52:55]
	v_mfma_f32_16x16x32_bf16 v[48:51], v[156:159], v[164:167], v[48:51]
	v_mfma_f32_16x16x32_bf16 v[36:39], v[148:151], v[172:175], v[36:39]
	v_mfma_f32_16x16x32_bf16 v[32:35], v[156:159], v[172:175], v[32:35]
	v_mfma_f32_16x16x32_bf16 v[20:23], v[148:151], v[180:183], v[20:23]
	v_mfma_f32_16x16x32_bf16 v[16:19], v[156:159], v[180:183], v[16:19]
	v_mfma_f32_16x16x32_bf16 v[4:7], v[148:151], v[188:191], v[4:7]
	v_mfma_f32_16x16x32_bf16 v[0:3], v[156:159], v[188:191], v[0:3]
	s_setprio 0
	s_barrier
	s_add_i32 s98, s98, 2
	s_add_u32 s6, s6, 0x100
	s_addc_u32 s7, s7, 0
	s_add_u32 s58, s58, 0x100
	s_addc_u32 s97, s97, 0
	s_cmp_gt_u32 s98, 5
	s_cbranch_scc0 .LBB0_395
.LBB0_398:
	s_lshl_b32 s6, s12, 8
	s_or_b32 s7, s6, s56
	s_lshl_b32 s6, s46, 10
	s_addk_i32 s6, 0x2100
	s_cmp_gt_i32 s46, 0
	v_lshl_add_u32 v214, s13, 8, v243
	s_cselect_b64 s[12:13], -1, 0
	s_cmp_lt_i32 s46, 1
	v_or_b32_e32 v212, s7, v244
	v_bitop3_b32 v120, s7, 56, v244 bitop3:0xc8
	s_cselect_b64 s[48:49], -1, 0
	s_add_i32 s7, s7, s6
	v_lshlrev_b32_e32 v192, 1, v120
	v_ashrrev_i32_e32 v215, 31, v214
	s_ashr_i32 s46, s7, 6
	v_lshl_add_u64 v[216:217], s[10:11], 0, v[192:193]
	v_lshlrev_b64 v[120:121], 7, v[214:215]
	s_ashr_i32 s47, s46, 31
	v_lshl_add_u64 v[120:121], v[216:217], 0, v[120:121]
	v_lshlrev_b64 v[122:123], 11, v[214:215]
	s_lshl_b64 s[60:61], s[46:47], 21
	v_lshl_add_u64 v[226:227], s[18:19], 0, v[122:123]
	v_lshl_add_u64 v[122:123], v[120:121], 0, s[60:61]
	global_load_dwordx4 v[188:191], v[122:123], off nt
	s_and_b64 vcc, exec, s[48:49]
	v_ashrrev_i32_e32 v213, 31, v212
	s_cbranch_vccnz .LBB0_400
	v_lshl_add_u64 v[122:123], v[212:213], 1, v[226:227]
	global_load_dwordx4 v[184:187], v[122:123], off nt
	s_branch .LBB0_401

; #define PG8_BAR __builtin_amdgcn_s_barrier()
; template <class Epi, class Sched, bool ALIGN_EPI = false, bool SP2 = false>
; __device__ __forceinline__ void gemm_phase(PG8_LAS unsigned char* lds, const Gemm g, const Sched& S, const Epi& E) {
;     ...
;         if constexpr (ALIGN_EPI) { if (wr == 0) PG8_BAR; }
.LBB0_417:
	s_and_b64 vcc, exec, s[20:21]
	s_cbranch_vccz .Lp3_nobar
	s_barrier
